# adds: UP epilogue issues its 8 conv-parameter loads together with the SW loads (one memory round trip, no wait behind the write-through halo stores)
# baseline (speedup 1.0000x reference)
; __device__ __forceinline__ void store_wt(void* p, const u32x4 v) { asm volatile("global_store_dwordx4 %0, %1, off sc1\n\ts_nop 2" :: "v"(p), "v"(v) : "memory"); }
;     __device__ __forceinline__ void operator()(f32x4 (&acc)[2][2][4][2], const pg8::Unit& u, int ui, int wr, int wc, int fr, int fq) const {
;         const int b = u.pm >> 4, lrow = wr * 128 + fr * 8, jc = u.pn * 128 + wc * 32 + fq * 8, swc = u.pn * 256 + wc * 32 + fq * 8;
;         {   f32x4 swa[2], swv[2];
; #pragma unroll
;             for (int n = 0; n < 2; ++n) { swa[n] = *(const f32x4*)(SW + (size_t)b * NUP + swc + n * 4); swv[n] = *(const f32x4*)(SW + (size_t)b * NUP + swc + 128 + n * 4); }
; #pragma unroll
;             for (int ai = 0; ai < 2; ++ai)
; #pragma unroll
;                 for (int m = 0; m < 4; ++m) { const float r = RSTD[ui * 256 + lrow + 4 * ai + m];
; #pragma unroll
;                     for (int n = 0; n < 2; ++n) { acc[ai][0][m][n] = acc[ai][0][m][n] * r + swa[n]; acc[ai][1][m][n] = acc[ai][1][m][n] * r + swv[n]; } }
;         }
;         {   const int kb = u.pm * 2 + wr;
;             if (fr == 0) { float* pa = HA + ((size_t)kb * 4) * DFF + jc; float* pv = HV + ((size_t)kb * 2) * DFF + jc;
;                 *(f32x4*)pa = acc[0][0][0][0]; *(f32x4*)(pa + 4) = acc[0][0][0][1]; *(f32x4*)(pa + DFF) = acc[0][0][1][0]; *(f32x4*)(pa + DFF + 4) = acc[0][0][1][1];
;                 *(f32x4*)pv = acc[0][1][0][0]; *(f32x4*)(pv + 4) = acc[0][1][0][1]; *(f32x4*)(pv + DFF) = acc[0][1][1][0]; *(f32x4*)(pv + DFF + 4) = acc[0][1][1][1]; }
;             if (fr == 15) { float* pa = HA + ((size_t)kb * 4 + 2) * DFF + jc;
;                 store_wt(pa, __builtin_bit_cast(u32x4, acc[1][0][2][0])); store_wt(pa + 4, __builtin_bit_cast(u32x4, acc[1][0][2][1])); store_wt(pa + DFF, __builtin_bit_cast(u32x4, acc[1][0][3][0])); store_wt(pa + DFF + 4, __builtin_bit_cast(u32x4, acc[1][0][3][1])); } }
; #pragma unroll
;         for (int n = 0; n < 2; ++n) {
;             const f32x4 cbv = *(const f32x4*)(cb + jc + n * 4), w0 = *(const f32x4*)(cw + jc + n * 4), w1 = *(const f32x4*)(cw + DFF + jc + n * 4), w2 = *(const f32x4*)(cw + 2 * DFF + jc + n * 4);
.LBB0_1259:
	v_mbcnt_lo_u32_b32 v130, -1, 0
	v_mbcnt_hi_u32_b32 v130, -1, v130
	s_lshl_b32 s27, s11, 8
	v_and_b32_e32 v172, 15, v130
	v_ashrrev_i32_e32 v130, 1, v130
	s_ashr_i32 s25, s10, 4
	v_and_b32_e32 v132, -8, v130
	s_or_b32 s27, s27, s83
	v_add_u32_e32 v130, s27, v132
	s_mul_hi_i32 s27, s25, 0xb000
	s_mul_i32 s25, s25, 0xb000
	s_add_u32 s34, s61, s25
	s_addc_u32 s35, s63, s27
	v_ashrrev_i32_e32 v131, 31, v130
	v_lshl_add_u64 v[130:131], v[130:131], 2, s[34:35]
	global_load_dwordx4 v[142:145], v[130:131], off offset:16
	global_load_dwordx4 v[150:153], v[130:131], off
	global_load_dwordx4 v[134:137], v[130:131], off offset:528
	global_load_dwordx4 v[138:141], v[130:131], off offset:512
	s_lshl_b32 s25, s92, 10
	v_lshl_or_b32 v0, v172, 3, s91
	s_add_i32 s25, s25, 0
	v_lshl_add_u32 v130, v0, 2, s25
	v_add_u32_e32 v130, 0x20400, v130
	ds_read_b128 v[154:157], v130
	ds_read_b128 v[146:149], v130 offset:16
	s_lshl_b32 s11, s11, 7
	s_or_b32 s11, s11, s83
	v_add_u32_e32 v170, s11, v132
	s_lshl_b32 s11, s10, 1
	s_waitcnt lgkmcnt(0)
	v_mov_b32_e32 v130, v149
	s_add_i32 s11, s11, s55
	v_cmp_lt_i32_e32 vcc, 14, v172
	v_ashrrev_i32_e32 v171, 31, v170
	v_lshlrev_b64 v[248:249], 2, v[170:171]
	v_lshl_add_u64 v[250:251], s[16:17], 0, v[248:249]
	v_lshl_add_u64 v[252:253], s[14:15], 0, v[248:249]
	global_load_dwordx4 v[212:215], v[250:251], off offset:16
	global_load_dwordx4 v[216:219], v[250:251], off
	global_load_dwordx4 v[220:223], v[252:253], off offset:16
	global_load_dwordx4 v[224:227], v[252:253], off
	v_lshl_add_u64 v[250:251], s[20:21], 0, v[248:249]
	v_lshl_add_u64 v[252:253], s[22:23], 0, v[248:249]
	global_load_dwordx4 v[228:231], v[250:251], off offset:16
	global_load_dwordx4 v[232:235], v[250:251], off
	global_load_dwordx4 v[236:239], v[252:253], off offset:16
	global_load_dwordx4 v[244:247], v[252:253], off
	s_waitcnt vmcnt(0)
	v_pk_fma_f32 v[8:9], v[8:9], v[148:149], v[144:145] op_sel_hi:[1,0,1]
	v_pk_fma_f32 v[44:45], v[44:45], v[148:149], v[152:153] op_sel_hi:[1,0,1]
	v_pk_fma_f32 v[42:43], v[42:43], v[148:149], v[150:151] op_sel_hi:[1,0,1]
	v_pk_fma_f32 v[6:7], v[6:7], v[148:149], v[142:143] op_sel_hi:[1,0,1]
	v_pk_fma_f32 v[40:41], v[40:41], v[130:131], v[152:153] op_sel_hi:[1,0,1]
	v_pk_fma_f32 v[38:39], v[38:39], v[130:131], v[150:151] op_sel_hi:[1,0,1]
	v_pk_fma_f32 v[4:5], v[4:5], v[130:131], v[144:145] op_sel_hi:[1,0,1]
	v_pk_fma_f32 v[2:3], v[2:3], v[130:131], v[142:143] op_sel_hi:[1,0,1]
	s_and_saveexec_b64 s[34:35], vcc
	s_xor_b64 s[34:35], exec, s[34:35]
	s_cbranch_execz .LBB0_1261
	s_mul_i32 s27, s11, 0x16000
	s_mul_hi_i32 s25, s11, 0x16000
	s_add_u32 s36, s70, s27
	s_addc_u32 s37, s71, s25
	v_lshl_add_u64 v[130:131], v[170:171], 2, s[36:37]
	s_mov_b64 s[36:37], 0xb000
	v_lshl_add_u64 v[132:133], v[130:131], 0, s[36:37]
	global_store_dwordx4 v[132:133], v[42:45], off sc1
	s_nop 2
	s_mov_b64 s[36:37], 0xb010
	v_lshl_add_u64 v[132:133], v[130:131], 0, s[36:37]
	global_store_dwordx4 v[132:133], v[6:9], off sc1
	s_nop 2
	s_mov_b64 s[36:37], 0x10800
	v_lshl_add_u64 v[132:133], v[130:131], 0, s[36:37]
	global_store_dwordx4 v[132:133], v[38:41], off sc1
	s_nop 2
	s_mov_b64 s[36:37], 0x10810
	v_lshl_add_u64 v[130:131], v[130:131], 0, s[36:37]
	global_store_dwordx4 v[130:131], v[2:5], off sc1
	s_nop 2

; __device__ __forceinline__ f32x4 silu4(const f32x4 p) { f32x4 r; r.x = siluf(p.x); r.y = siluf(p.y); r.z = siluf(p.z); r.w = siluf(p.w); return r; }
;     __device__ __forceinline__ void operator()(f32x4 (&acc)[2][2][4][2], const pg8::Unit& u, int ui, int wr, int wc, int fr, int fq) const {
;     ...
;                 for (int m = 0; m < 4; ++m) { const float r = RSTD[ui * 256 + lrow + 4 * ai + m];
; #pragma unroll
;                     for (int n = 0; n < 2; ++n) { acc[ai][0][m][n] = acc[ai][0][m][n] * r + swa[n]; acc[ai][1][m][n] = acc[ai][1][m][n] * r + swv[n]; } }
;         }
;         {   const int kb = u.pm * 2 + wr;
;             if (fr == 0) { float* pa = HA + ((size_t)kb * 4) * DFF + jc; float* pv = HV + ((size_t)kb * 2) * DFF + jc;
;                 *(f32x4*)pa = acc[0][0][0][0]; *(f32x4*)(pa + 4) = acc[0][0][0][1]; *(f32x4*)(pa + DFF) = acc[0][0][1][0]; *(f32x4*)(pa + DFF + 4) = acc[0][0][1][1];
;                 *(f32x4*)pv = acc[0][1][0][0]; *(f32x4*)(pv + 4) = acc[0][1][0][1]; *(f32x4*)(pv + DFF) = acc[0][1][1][0]; *(f32x4*)(pv + DFF + 4) = acc[0][1][1][1]; }
;             if (fr == 15) { float* pa = HA + ((size_t)kb * 4 + 2) * DFF + jc;
;                 store_wt(pa, __builtin_bit_cast(u32x4, acc[1][0][2][0])); store_wt(pa + 4, __builtin_bit_cast(u32x4, acc[1][0][2][1])); store_wt(pa + DFF, __builtin_bit_cast(u32x4, acc[1][0][3][0])); store_wt(pa + DFF + 4, __builtin_bit_cast(u32x4, acc[1][0][3][1])); } }
; #pragma unroll
;         for (int n = 0; n < 2; ++n) {
;             const f32x4 cbv = *(const f32x4*)(cb + jc + n * 4), w0 = *(const f32x4*)(cw + jc + n * 4), w1 = *(const f32x4*)(cw + DFF + jc + n * 4), w2 = *(const f32x4*)(cw + 2 * DFF + jc + n * 4);
;             f32x4 p2, p1;
;             { const f32x4 x6 = acc[1][0][2][n], x7 = acc[1][0][3][n];
;               p2 = (f32x4){dpp_z<0x111>(x6.x), dpp_z<0x111>(x6.y), dpp_z<0x111>(x6.z), dpp_z<0x111>(x6.w)};
;               p1 = (f32x4){dpp_z<0x111>(x7.x), dpp_z<0x111>(x7.y), dpp_z<0x111>(x7.z), dpp_z<0x111>(x7.w)}; }
; #pragma unroll
;             for (int j = 0; j < 8; ++j) { const f32x4 x = acc[j >> 2][0][j & 3][n];
;                 const f32x4 cv = cbv + w0 * p2 + w1 * p1 + w2 * x;
;                 acc[j >> 2][1][j & 3][n] = silu4(cv) * acc[j >> 2][1][j & 3][n];
.LBB0_1265:
	s_or_b64 exec, exec, s[34:35]
	v_mov_b32_e32 v194, v148
	v_mov_b32_e32 v195, v148
	v_pk_fma_f32 v[116:117], v[94:95], v[156:157], v[138:139] op_sel_hi:[1,0,1]
	v_pk_fma_f32 v[94:95], v[108:109], v[156:157], v[144:145] op_sel_hi:[1,0,1]
	v_pk_fma_f32 v[108:109], v[90:91], v[156:157], v[134:135] op_sel_hi:[1,0,1]
	v_mov_b32_e32 v90, v157
	v_mov_b32_e32 v196, v149
	v_mov_b32_e32 v197, v149
	v_pk_fma_f32 v[184:185], v[112:113], v[156:157], v[152:153] op_sel_hi:[1,0,1]
	v_pk_fma_f32 v[186:187], v[110:111], v[156:157], v[150:151] op_sel_hi:[1,0,1]
	v_pk_fma_f32 v[114:115], v[96:97], v[156:157], v[140:141] op_sel_hi:[1,0,1]
	v_pk_fma_f32 v[96:97], v[106:107], v[156:157], v[142:143] op_sel_hi:[1,0,1]
	v_pk_fma_f32 v[106:107], v[92:93], v[156:157], v[136:137] op_sel_hi:[1,0,1]
	v_pk_fma_f32 v[190:191], v[86:87], v[90:91], v[138:139] op_sel_hi:[1,0,1]
	v_pk_fma_f32 v[86:87], v[100:101], v[90:91], v[144:145] op_sel_hi:[1,0,1]
	v_pk_fma_f32 v[100:101], v[82:83], v[90:91], v[134:135] op_sel_hi:[1,0,1]
	v_pk_fma_f32 v[156:157], v[80:81], v[146:147], v[152:153] op_sel_hi:[1,0,1]
	v_pk_fma_f32 v[80:81], v[76:77], v[146:147], v[144:145] op_sel_hi:[1,0,1]
	v_pk_fma_f32 v[82:83], v[50:51], v[146:147], v[134:135] op_sel:[0,1,0]
	v_mov_b32_e32 v50, v148
	v_mov_b32_e32 v51, v148
	v_pk_fma_f32 v[76:77], v[18:19], v[194:195], v[134:135]
	v_pk_fma_f32 v[176:177], v[104:105], v[90:91], v[152:153] op_sel_hi:[1,0,1]
	v_pk_fma_f32 v[154:155], v[78:79], v[146:147], v[150:151] op_sel_hi:[1,0,1]
	v_pk_fma_f32 v[180:181], v[62:63], v[146:147], v[138:139] op_sel_hi:[1,0,1]
	v_pk_fma_f32 v[78:79], v[74:75], v[146:147], v[142:143] op_sel_hi:[1,0,1]
	v_pk_fma_f32 v[152:153], v[72:73], v[146:147], v[152:153] op_sel:[0,1,0]
	v_pk_fma_f32 v[172:173], v[54:55], v[146:147], v[138:139] op_sel:[0,1,0]
	v_pk_fma_f32 v[72:73], v[68:69], v[146:147], v[144:145] op_sel:[0,1,0]
	v_pk_fma_f32 v[144:145], v[22:23], v[194:195], v[138:139]
	v_pk_fma_f32 v[74:75], v[20:21], v[50:51], v[136:137]
	v_mov_b32_e32 v148, v149
	v_pk_fma_f32 v[138:139], v[14:15], v[196:197], v[138:139]
	v_pk_fma_f32 v[178:179], v[102:103], v[90:91], v[150:151] op_sel_hi:[1,0,1]
	v_pk_fma_f32 v[188:189], v[88:89], v[90:91], v[140:141] op_sel_hi:[1,0,1]
	v_pk_fma_f32 v[88:89], v[98:99], v[90:91], v[142:143] op_sel_hi:[1,0,1]
	v_pk_fma_f32 v[98:99], v[84:85], v[90:91], v[136:137] op_sel_hi:[1,0,1]
	v_pk_fma_f32 v[182:183], v[64:65], v[146:147], v[140:141] op_sel_hi:[1,0,1]
	v_pk_fma_f32 v[150:151], v[70:71], v[146:147], v[150:151] op_sel:[0,1,0]
	v_pk_fma_f32 v[174:175], v[56:57], v[146:147], v[140:141] op_sel:[0,1,0]
	v_pk_fma_f32 v[70:71], v[66:67], v[146:147], v[142:143] op_sel:[0,1,0]
	v_pk_fma_f32 v[84:85], v[52:53], v[146:147], v[136:137] op_sel:[0,1,0]
	v_pk_fma_f32 v[142:143], v[24:25], v[50:51], v[140:141]
	v_pk_fma_f32 v[140:141], v[16:17], v[148:149], v[140:141]
	v_pk_fma_f32 v[66:67], v[12:13], v[148:149], v[136:137]
	v_pk_fma_f32 v[68:69], v[10:11], v[196:197], v[134:135]
	v_mov_b32_e32 v10, v212
	v_mov_b32_e32 v11, v213
	v_mov_b32_e32 v12, v214
	v_mov_b32_e32 v13, v215
	v_mov_b32_e32 v50, v216
	v_mov_b32_e32 v51, v217
	v_mov_b32_e32 v52, v218
	v_mov_b32_e32 v53, v219
	v_mov_b32_e32 v14, v220
	v_mov_b32_e32 v15, v221
	v_mov_b32_e32 v16, v222
	v_mov_b32_e32 v17, v223
	v_mov_b32_e32 v54, v224
	v_mov_b32_e32 v55, v225
	v_mov_b32_e32 v56, v226
	v_mov_b32_e32 v57, v227
	v_pk_fma_f32 v[90:91], v[58:59], v[146:147], v[134:135] op_sel_hi:[1,0,1]
	v_mov_b32_e32 v22, v228
	v_mov_b32_e32 v23, v229
	v_mov_b32_e32 v24, v230
	v_mov_b32_e32 v25, v231
	v_mov_b32_e32 v62, v232
	v_mov_b32_e32 v63, v233
	v_mov_b32_e32 v64, v234
	v_mov_b32_e32 v65, v235
	v_pk_fma_f32 v[92:93], v[60:61], v[146:147], v[136:137] op_sel_hi:[1,0,1]
	v_mov_b32_e32 v18, v236
	v_mov_b32_e32 v19, v237
	v_mov_b32_e32 v20, v238
	v_mov_b32_e32 v21, v239
	v_mov_b32_e32 v58, v244
	v_mov_b32_e32 v59, v245
	v_mov_b32_e32 v60, v246
	v_mov_b32_e32 v61, v247
	v_mov_b32_e32 v102, 0
	v_mov_b32_e32 v103, 0
	v_mov_b32_e32 v104, 0
	v_mov_b32_e32 v105, 0
	v_mov_b32_dpp v102, v42 row_shr:1 row_mask:0xf bank_mask:0xf
	v_mov_b32_dpp v103, v43 row_shr:1 row_mask:0xf bank_mask:0xf
	v_mov_b32_dpp v104, v44 row_shr:1 row_mask:0xf bank_mask:0xf
	v_mov_b32_dpp v105, v45 row_shr:1 row_mask:0xf bank_mask:0xf
	v_mov_b32_e32 v110, 0
	v_mov_b32_e32 v111, 0
	v_mov_b32_e32 v112, 0
	v_mov_b32_e32 v113, 0
	v_mov_b32_dpp v110, v38 row_shr:1 row_mask:0xf bank_mask:0xf
	v_mov_b32_dpp v111, v39 row_shr:1 row_mask:0xf bank_mask:0xf
	v_mov_b32_dpp v112, v40 row_shr:1 row_mask:0xf bank_mask:0xf
	v_mov_b32_dpp v113, v41 row_shr:1 row_mask:0xf bank_mask:0xf
	s_mul_hi_i32 s11, s10, 0x2c0000
	s_mul_i32 s10, s10, 0x2c0000
	s_add_u32 s10, s67, s10
	s_addc_u32 s11, s68, s11
	s_andn2_b64 vcc, exec, s[6:7]
	v_pk_fma_f32 v[104:105], v[56:57], v[104:105], v[52:53]
	v_pk_fma_f32 v[102:103], v[54:55], v[102:103], v[50:51]
	v_pk_fma_f32 v[104:105], v[64:65], v[112:113], v[104:105]
	v_pk_fma_f32 v[102:103], v[62:63], v[110:111], v[102:103]
	v_pk_fma_f32 v[112:113], v[56:57], v[112:113], v[52:53]
	v_pk_fma_f32 v[104:105], v[128:129], v[60:61], v[104:105]
	v_pk_fma_f32 v[102:103], v[126:127], v[58:59], v[102:103]
	v_mul_f32_e32 v136, 0xbfb8aa3b, v104
	v_mul_f32_e32 v134, 0xbfb8aa3b, v102
	v_mul_f32_e32 v135, 0xbfb8aa3b, v103
	v_mul_f32_e32 v137, 0xbfb8aa3b, v105
	v_exp_f32_e32 v134, v134
	v_exp_f32_e32 v135, v135
	v_exp_f32_e32 v136, v136
	v_exp_f32_e32 v137, v137
	v_add_f32_e32 v134, 1.0, v134
	v_add_f32_e32 v135, 1.0, v135
	v_add_f32_e32 v136, 1.0, v136
	v_add_f32_e32 v137, 1.0, v137
	v_rcp_f32_e32 v134, v134
	v_rcp_f32_e32 v135, v135
	v_rcp_f32_e32 v136, v136
	v_rcp_f32_e32 v137, v137
; __device__ __forceinline__ f32x4 silu4(const f32x4 p) { f32x4 r; r.x = siluf(p.x); r.y = siluf(p.y); r.z = siluf(p.z); r.w = siluf(p.w); return r; }
; template <int CTRL> __device__ __forceinline__ float dpp_z(float v) { return __int_as_float(__builtin_amdgcn_update_dpp(0, __float_as_int(v), CTRL, 0xf, 0xf, false)); }
;     __device__ __forceinline__ void operator()(f32x4 (&acc)[2][2][4][2], const pg8::Unit& u, int ui, int wr, int wc, int fr, int fq) const {
;     ...
;         for (int n = 0; n < 2; ++n) {
;             const f32x4 cbv = *(const f32x4*)(cb + jc + n * 4), w0 = *(const f32x4*)(cw + jc + n * 4), w1 = *(const f32x4*)(cw + DFF + jc + n * 4), w2 = *(const f32x4*)(cw + 2 * DFF + jc + n * 4);
;             f32x4 p2, p1;
;             { const f32x4 x6 = acc[1][0][2][n], x7 = acc[1][0][3][n];
;               p2 = (f32x4){dpp_z<0x111>(x6.x), dpp_z<0x111>(x6.y), dpp_z<0x111>(x6.z), dpp_z<0x111>(x6.w)};
;               p1 = (f32x4){dpp_z<0x111>(x7.x), dpp_z<0x111>(x7.y), dpp_z<0x111>(x7.z), dpp_z<0x111>(x7.w)}; }
; #pragma unroll
;             for (int j = 0; j < 8; ++j) { const f32x4 x = acc[j >> 2][0][j & 3][n];
;                 const f32x4 cv = cbv + w0 * p2 + w1 * p1 + w2 * x;
;                 acc[j >> 2][1][j & 3][n] = silu4(cv) * acc[j >> 2][1][j & 3][n];
;                 p2 = p1; p1 = x; }
	v_pk_fma_f32 v[110:111], v[54:55], v[110:111], v[50:51]
	v_pk_fma_f32 v[112:113], v[128:129], v[64:65], v[112:113]
	v_pk_fma_f32 v[110:111], v[126:127], v[62:63], v[110:111]
	v_pk_mul_f32 v[104:105], v[104:105], v[136:137]
	v_pk_mul_f32 v[134:135], v[102:103], v[134:135]
	v_pk_fma_f32 v[112:113], v[120:121], v[60:61], v[112:113]
	v_pk_fma_f32 v[110:111], v[118:119], v[58:59], v[110:111]
	v_pk_mul_f32 v[102:103], v[132:133], v[104:105]
	v_pk_mul_f32 v[104:105], v[130:131], v[134:135]
	v_mul_f32_e32 v130, 0xbfb8aa3b, v110
	v_mul_f32_e32 v131, 0xbfb8aa3b, v111
	v_mul_f32_e32 v132, 0xbfb8aa3b, v112
	v_mul_f32_e32 v133, 0xbfb8aa3b, v113
	v_exp_f32_e32 v130, v130
	v_exp_f32_e32 v131, v131
	v_exp_f32_e32 v132, v132
	v_exp_f32_e32 v133, v133
	v_add_f32_e32 v130, 1.0, v130
	v_add_f32_e32 v131, 1.0, v131
	v_add_f32_e32 v132, 1.0, v132
	v_add_f32_e32 v133, 1.0, v133
	v_rcp_f32_e32 v130, v130
	v_rcp_f32_e32 v131, v131
	v_rcp_f32_e32 v132, v132
	v_rcp_f32_e32 v133, v133
	v_pk_mul_f32 v[130:131], v[110:111], v[130:131]
	v_pk_mul_f32 v[112:113], v[112:113], v[132:133]
	s_nop 0
	v_pk_mul_f32 v[110:111], v[124:125], v[112:113]
	v_pk_mul_f32 v[112:113], v[122:123], v[130:131]
	v_pk_fma_f32 v[122:123], v[128:129], v[56:57], v[52:53]
	v_pk_fma_f32 v[124:125], v[126:127], v[54:55], v[50:51]
	v_pk_fma_f32 v[122:123], v[120:121], v[64:65], v[122:123]
	v_pk_fma_f32 v[124:125], v[118:119], v[62:63], v[124:125]
	v_pk_fma_f32 v[122:123], v[184:185], v[60:61], v[122:123]
	v_pk_fma_f32 v[124:125], v[186:187], v[58:59], v[124:125]
	v_mul_f32_e32 v128, 0xbfb8aa3b, v122
	v_mul_f32_e32 v126, 0xbfb8aa3b, v124
	v_mul_f32_e32 v127, 0xbfb8aa3b, v125
	v_mul_f32_e32 v129, 0xbfb8aa3b, v123
	v_exp_f32_e32 v126, v126
	v_exp_f32_e32 v127, v127
	v_exp_f32_e32 v128, v128
	v_exp_f32_e32 v129, v129
	v_add_f32_e32 v126, 1.0, v126
	v_add_f32_e32 v127, 1.0, v127
	v_add_f32_e32 v128, 1.0, v128
	v_add_f32_e32 v129, 1.0, v129
	v_rcp_f32_e32 v126, v126
	v_rcp_f32_e32 v127, v127
	v_rcp_f32_e32 v128, v128
	v_rcp_f32_e32 v129, v129
	v_pk_fma_f32 v[120:121], v[120:121], v[56:57], v[52:53]
	v_pk_fma_f32 v[118:119], v[118:119], v[54:55], v[50:51]
	v_pk_fma_f32 v[120:121], v[184:185], v[64:65], v[120:121]
	v_pk_fma_f32 v[118:119], v[186:187], v[62:63], v[118:119]
	v_pk_mul_f32 v[122:123], v[122:123], v[128:129]
	v_pk_mul_f32 v[124:125], v[124:125], v[126:127]
	v_pk_fma_f32 v[120:121], v[176:177], v[60:61], v[120:121]
	v_pk_fma_f32 v[118:119], v[178:179], v[58:59], v[118:119]
	v_pk_mul_f32 v[114:115], v[114:115], v[122:123]
	v_pk_mul_f32 v[116:117], v[116:117], v[124:125]
	v_mul_f32_e32 v122, 0xbfb8aa3b, v118
	v_mul_f32_e32 v123, 0xbfb8aa3b, v119
	v_mul_f32_e32 v124, 0xbfb8aa3b, v120
	v_mul_f32_e32 v125, 0xbfb8aa3b, v121
	v_exp_f32_e32 v122, v122
	v_exp_f32_e32 v123, v123
	v_exp_f32_e32 v124, v124
	v_exp_f32_e32 v125, v125
	v_add_f32_e32 v122, 1.0, v122
	v_add_f32_e32 v123, 1.0, v123
	v_add_f32_e32 v124, 1.0, v124
	v_add_f32_e32 v125, 1.0, v125
	v_rcp_f32_e32 v122, v122
	v_rcp_f32_e32 v123, v123
	v_rcp_f32_e32 v124, v124
	v_rcp_f32_e32 v125, v125
	v_pk_mul_f32 v[122:123], v[118:119], v[122:123]
	v_pk_mul_f32 v[120:121], v[120:121], v[124:125]
	s_nop 0
	v_pk_mul_f32 v[118:119], v[188:189], v[120:121]
	v_pk_mul_f32 v[120:121], v[190:191], v[122:123]
	v_pk_fma_f32 v[122:123], v[186:187], v[54:55], v[50:51]
	v_pk_fma_f32 v[124:125], v[184:185], v[56:57], v[52:53]
	v_pk_fma_f32 v[122:123], v[178:179], v[62:63], v[122:123]
	v_pk_fma_f32 v[124:125], v[176:177], v[64:65], v[124:125]
	v_pk_fma_f32 v[122:123], v[154:155], v[58:59], v[122:123]
	v_pk_fma_f32 v[124:125], v[156:157], v[60:61], v[124:125]
	v_mul_f32_e32 v126, 0xbfb8aa3b, v122
	v_mul_f32_e32 v127, 0xbfb8aa3b, v123
	v_mul_f32_e32 v128, 0xbfb8aa3b, v124
	v_mul_f32_e32 v129, 0xbfb8aa3b, v125
	v_exp_f32_e32 v126, v126
	v_exp_f32_e32 v127, v127
	v_exp_f32_e32 v128, v128
	v_exp_f32_e32 v129, v129
	v_add_f32_e32 v126, 1.0, v126
	v_add_f32_e32 v127, 1.0, v127
	v_add_f32_e32 v128, 1.0, v128
	v_add_f32_e32 v129, 1.0, v129
	v_rcp_f32_e32 v126, v126
	v_rcp_f32_e32 v127, v127
	v_rcp_f32_e32 v128, v128
	v_rcp_f32_e32 v129, v129
	v_pk_mul_f32 v[126:127], v[122:123], v[126:127]
	v_pk_mul_f32 v[124:125], v[124:125], v[128:129]
	s_nop 0
	v_pk_mul_f32 v[122:123], v[182:183], v[124:125]
	v_pk_mul_f32 v[124:125], v[180:181], v[126:127]
	v_pk_fma_f32 v[126:127], v[176:177], v[56:57], v[52:53]
	v_pk_fma_f32 v[128:129], v[178:179], v[54:55], v[50:51]
	v_pk_fma_f32 v[126:127], v[156:157], v[64:65], v[126:127]
	v_pk_fma_f32 v[128:129], v[154:155], v[62:63], v[128:129]
	v_pk_fma_f32 v[126:127], v[152:153], v[60:61], v[126:127]
	v_pk_fma_f32 v[128:129], v[150:151], v[58:59], v[128:129]
	v_mul_f32_e32 v132, 0xbfb8aa3b, v126
	v_mul_f32_e32 v130, 0xbfb8aa3b, v128
	v_mul_f32_e32 v131, 0xbfb8aa3b, v129
	v_mul_f32_e32 v133, 0xbfb8aa3b, v127
	v_exp_f32_e32 v130, v130
	v_exp_f32_e32 v131, v131
	v_exp_f32_e32 v132, v132
	v_exp_f32_e32 v133, v133
	v_add_f32_e32 v130, 1.0, v130
	v_add_f32_e32 v131, 1.0, v131
	v_add_f32_e32 v132, 1.0, v132
	v_add_f32_e32 v133, 1.0, v133
	v_rcp_f32_e32 v130, v130
	v_rcp_f32_e32 v131, v131
	v_rcp_f32_e32 v132, v132
	v_rcp_f32_e32 v133, v133
	v_pk_mul_f32 v[128:129], v[128:129], v[130:131]
	v_pk_fma_f32 v[130:131], v[156:157], v[56:57], v[52:53]
	v_pk_mul_f32 v[126:127], v[126:127], v[132:133]
	v_pk_fma_f32 v[132:133], v[154:155], v[54:55], v[50:51]
	v_pk_fma_f32 v[130:131], v[152:153], v[64:65], v[130:131]
	v_pk_fma_f32 v[132:133], v[150:151], v[62:63], v[132:133]
	v_pk_fma_f32 v[52:53], v[152:153], v[56:57], v[52:53]
	v_pk_fma_f32 v[50:51], v[150:151], v[54:55], v[50:51]
	v_pk_fma_f32 v[130:131], v[44:45], v[60:61], v[130:131]
; __device__ __forceinline__ f32x4 silu4(const f32x4 p) { f32x4 r; r.x = siluf(p.x); r.y = siluf(p.y); r.z = siluf(p.z); r.w = siluf(p.w); return r; }
; template <int CTRL> __device__ __forceinline__ float dpp_z(float v) { return __int_as_float(__builtin_amdgcn_update_dpp(0, __float_as_int(v), CTRL, 0xf, 0xf, false)); }
;     __device__ __forceinline__ void operator()(f32x4 (&acc)[2][2][4][2], const pg8::Unit& u, int ui, int wr, int wc, int fr, int fq) const {
;     ...
;         for (int n = 0; n < 2; ++n) {
;             const f32x4 cbv = *(const f32x4*)(cb + jc + n * 4), w0 = *(const f32x4*)(cw + jc + n * 4), w1 = *(const f32x4*)(cw + DFF + jc + n * 4), w2 = *(const f32x4*)(cw + 2 * DFF + jc + n * 4);
;             f32x4 p2, p1;
;             { const f32x4 x6 = acc[1][0][2][n], x7 = acc[1][0][3][n];
;               p2 = (f32x4){dpp_z<0x111>(x6.x), dpp_z<0x111>(x6.y), dpp_z<0x111>(x6.z), dpp_z<0x111>(x6.w)};
;               p1 = (f32x4){dpp_z<0x111>(x7.x), dpp_z<0x111>(x7.y), dpp_z<0x111>(x7.z), dpp_z<0x111>(x7.w)}; }
; #pragma unroll
;             for (int j = 0; j < 8; ++j) { const f32x4 x = acc[j >> 2][0][j & 3][n];
;                 const f32x4 cv = cbv + w0 * p2 + w1 * p1 + w2 * x;
;                 acc[j >> 2][1][j & 3][n] = silu4(cv) * acc[j >> 2][1][j & 3][n];
;                 p2 = p1; p1 = x; }
	v_pk_fma_f32 v[132:133], v[42:43], v[58:59], v[132:133]
	v_pk_fma_f32 v[44:45], v[44:45], v[64:65], v[52:53]
	v_pk_fma_f32 v[42:43], v[42:43], v[62:63], v[50:51]
	v_pk_fma_f32 v[40:41], v[40:41], v[60:61], v[44:45]
	v_pk_fma_f32 v[38:39], v[38:39], v[58:59], v[42:43]
	v_mul_f32_e32 v44, 0xbfb8aa3b, v40
	v_mul_f32_e32 v42, 0xbfb8aa3b, v38
	v_mul_f32_e32 v43, 0xbfb8aa3b, v39
	v_mul_f32_e32 v45, 0xbfb8aa3b, v41
	v_exp_f32_e32 v42, v42
	v_exp_f32_e32 v43, v43
	v_exp_f32_e32 v44, v44
	v_exp_f32_e32 v45, v45
	v_add_f32_e32 v42, 1.0, v42
	v_add_f32_e32 v43, 1.0, v43
	v_add_f32_e32 v44, 1.0, v44
	v_add_f32_e32 v45, 1.0, v45
	v_rcp_f32_e32 v42, v42
	v_rcp_f32_e32 v43, v43
	v_rcp_f32_e32 v44, v44
	v_rcp_f32_e32 v45, v45
	v_mov_b32_e32 v50, 0
	v_pk_mul_f32 v[42:43], v[38:39], v[42:43]
	v_mov_b32_e32 v51, 0
	v_pk_mul_f32 v[40:41], v[40:41], v[44:45]
	v_mov_b32_e32 v44, 0
	v_pk_mul_f32 v[38:39], v[140:141], v[40:41]
	v_pk_mul_f32 v[40:41], v[138:139], v[42:43]
	v_mov_b32_e32 v42, 0
	v_mov_b32_e32 v43, 0
	v_mov_b32_e32 v45, 0
	v_mov_b32_dpp v42, v6 row_shr:1 row_mask:0xf bank_mask:0xf
	v_mov_b32_dpp v43, v7 row_shr:1 row_mask:0xf bank_mask:0xf
	v_mov_b32_dpp v44, v8 row_shr:1 row_mask:0xf bank_mask:0xf
	v_mov_b32_dpp v45, v9 row_shr:1 row_mask:0xf bank_mask:0xf
	v_mov_b32_e32 v52, 0
	v_mov_b32_e32 v53, 0
	v_mov_b32_dpp v50, v2 row_shr:1 row_mask:0xf bank_mask:0xf
	v_mov_b32_dpp v51, v3 row_shr:1 row_mask:0xf bank_mask:0xf
	v_mov_b32_dpp v52, v4 row_shr:1 row_mask:0xf bank_mask:0xf
	v_mov_b32_dpp v53, v5 row_shr:1 row_mask:0xf bank_mask:0xf
	v_pk_fma_f32 v[44:45], v[16:17], v[44:45], v[12:13]
	v_pk_fma_f32 v[42:43], v[14:15], v[42:43], v[10:11]
	v_pk_fma_f32 v[44:45], v[24:25], v[52:53], v[44:45]
	v_pk_fma_f32 v[42:43], v[22:23], v[50:51], v[42:43]
	v_pk_fma_f32 v[44:45], v[32:33], v[20:21], v[44:45]
	v_pk_fma_f32 v[42:43], v[30:31], v[18:19], v[42:43]
	v_mul_f32_e32 v56, 0xbfb8aa3b, v44
	v_mul_f32_e32 v54, 0xbfb8aa3b, v42
	v_mul_f32_e32 v55, 0xbfb8aa3b, v43
	v_mul_f32_e32 v57, 0xbfb8aa3b, v45
	v_exp_f32_e32 v54, v54
	v_exp_f32_e32 v55, v55
	v_exp_f32_e32 v56, v56
	v_exp_f32_e32 v57, v57
	v_add_f32_e32 v54, 1.0, v54
	v_add_f32_e32 v55, 1.0, v55
	v_add_f32_e32 v56, 1.0, v56
	v_add_f32_e32 v57, 1.0, v57
	v_rcp_f32_e32 v54, v54
	v_rcp_f32_e32 v55, v55
	v_rcp_f32_e32 v56, v56
	v_rcp_f32_e32 v57, v57
	v_mul_f32_e32 v134, 0xbfb8aa3b, v132
	v_pk_mul_f32 v[54:55], v[42:43], v[54:55]
	v_mul_f32_e32 v135, 0xbfb8aa3b, v133
	v_pk_mul_f32 v[44:45], v[44:45], v[56:57]
	v_mul_f32_e32 v136, 0xbfb8aa3b, v130
	v_pk_mul_f32 v[42:43], v[48:49], v[44:45]
	v_pk_mul_f32 v[44:45], v[46:47], v[54:55]
	v_pk_fma_f32 v[46:47], v[16:17], v[52:53], v[12:13]
	v_pk_fma_f32 v[48:49], v[14:15], v[50:51], v[10:11]
	v_pk_fma_f32 v[46:47], v[32:33], v[24:25], v[46:47]
	v_pk_fma_f32 v[48:49], v[30:31], v[22:23], v[48:49]
	v_pk_fma_f32 v[46:47], v[28:29], v[20:21], v[46:47]
	v_pk_fma_f32 v[48:49], v[26:27], v[18:19], v[48:49]
	v_mul_f32_e32 v52, 0xbfb8aa3b, v46
	v_mul_f32_e32 v50, 0xbfb8aa3b, v48
	v_mul_f32_e32 v51, 0xbfb8aa3b, v49
	v_mul_f32_e32 v53, 0xbfb8aa3b, v47
	v_exp_f32_e32 v50, v50
	v_exp_f32_e32 v51, v51
	v_exp_f32_e32 v52, v52
	v_exp_f32_e32 v53, v53
	v_add_f32_e32 v50, 1.0, v50
	v_add_f32_e32 v51, 1.0, v51
	v_add_f32_e32 v52, 1.0, v52
	v_add_f32_e32 v53, 1.0, v53
	v_rcp_f32_e32 v50, v50
	v_rcp_f32_e32 v51, v51
	v_rcp_f32_e32 v52, v52
	v_rcp_f32_e32 v53, v53
	v_pk_fma_f32 v[32:33], v[32:33], v[16:17], v[12:13]
	v_pk_fma_f32 v[30:31], v[30:31], v[14:15], v[10:11]
	v_pk_fma_f32 v[32:33], v[28:29], v[24:25], v[32:33]
	v_pk_fma_f32 v[30:31], v[26:27], v[22:23], v[30:31]
	v_pk_mul_f32 v[46:47], v[46:47], v[52:53]
	v_pk_mul_f32 v[48:49], v[48:49], v[50:51]
	v_pk_fma_f32 v[32:33], v[94:95], v[20:21], v[32:33]
	v_pk_fma_f32 v[30:31], v[96:97], v[18:19], v[30:31]
	v_pk_mul_f32 v[36:37], v[36:37], v[46:47]
	v_pk_mul_f32 v[34:35], v[34:35], v[48:49]
	v_mul_f32_e32 v46, 0xbfb8aa3b, v30
	v_mul_f32_e32 v47, 0xbfb8aa3b, v31
	v_mul_f32_e32 v48, 0xbfb8aa3b, v32
	v_mul_f32_e32 v49, 0xbfb8aa3b, v33
	v_exp_f32_e32 v46, v46
	v_exp_f32_e32 v47, v47
	v_exp_f32_e32 v48, v48
	v_exp_f32_e32 v49, v49
	v_add_f32_e32 v46, 1.0, v46
	v_add_f32_e32 v47, 1.0, v47
	v_add_f32_e32 v48, 1.0, v48
	v_add_f32_e32 v49, 1.0, v49
	v_rcp_f32_e32 v46, v46
	v_rcp_f32_e32 v47, v47
	v_rcp_f32_e32 v48, v48
	v_rcp_f32_e32 v49, v49
	v_pk_fma_f32 v[28:29], v[28:29], v[16:17], v[12:13]
	v_pk_fma_f32 v[26:27], v[26:27], v[14:15], v[10:11]
	v_pk_fma_f32 v[28:29], v[94:95], v[24:25], v[28:29]
	v_pk_fma_f32 v[26:27], v[96:97], v[22:23], v[26:27]
	v_pk_mul_f32 v[32:33], v[32:33], v[48:49]
	v_pk_mul_f32 v[46:47], v[30:31], v[46:47]
	v_pk_fma_f32 v[28:29], v[86:87], v[20:21], v[28:29]
	v_pk_fma_f32 v[26:27], v[88:89], v[18:19], v[26:27]
	v_pk_mul_f32 v[30:31], v[106:107], v[32:33]
	v_pk_mul_f32 v[32:33], v[108:109], v[46:47]
	v_mul_f32_e32 v46, 0xbfb8aa3b, v26
	v_mul_f32_e32 v47, 0xbfb8aa3b, v27
	v_mul_f32_e32 v48, 0xbfb8aa3b, v28
	v_mul_f32_e32 v49, 0xbfb8aa3b, v29
	v_exp_f32_e32 v46, v46
	v_exp_f32_e32 v47, v47
	v_exp_f32_e32 v48, v48
	v_exp_f32_e32 v49, v49
	v_add_f32_e32 v46, 1.0, v46
	v_add_f32_e32 v47, 1.0, v47
	v_add_f32_e32 v48, 1.0, v48
	v_add_f32_e32 v49, 1.0, v49
	v_rcp_f32_e32 v46, v46
	v_rcp_f32_e32 v47, v47
	v_rcp_f32_e32 v48, v48
	v_rcp_f32_e32 v49, v49
	v_mul_f32_e32 v137, 0xbfb8aa3b, v131
	v_pk_mul_f32 v[46:47], v[26:27], v[46:47]
	v_exp_f32_e32 v134, v134
	v_pk_mul_f32 v[28:29], v[28:29], v[48:49]
	v_pk_fma_f32 v[48:49], v[94:95], v[16:17], v[12:13]
	v_pk_mul_f32 v[26:27], v[98:99], v[28:29]
	v_pk_mul_f32 v[28:29], v[100:101], v[46:47]
	v_pk_fma_f32 v[46:47], v[96:97], v[14:15], v[10:11]
	v_pk_fma_f32 v[48:49], v[86:87], v[24:25], v[48:49]
; __device__ __forceinline__ u32x4 pack8(const f32x4 a, const f32x4 b) { u32x4 w; w.x = cvt_pk_bf16(a.x, a.y); w.y = cvt_pk_bf16(a.z, a.w); w.z = cvt_pk_bf16(b.x, b.y); w.w = cvt_pk_bf16(b.z, b.w); return w; }
; __device__ __forceinline__ f32x4 silu4(const f32x4 p) { f32x4 r; r.x = siluf(p.x); r.y = siluf(p.y); r.z = siluf(p.z); r.w = siluf(p.w); return r; }
; template <int CTRL> __device__ __forceinline__ float dpp_z(float v) { return __int_as_float(__builtin_amdgcn_update_dpp(0, __float_as_int(v), CTRL, 0xf, 0xf, false)); }
;     __device__ __forceinline__ void operator()(f32x4 (&acc)[2][2][4][2], const pg8::Unit& u, int ui, int wr, int wc, int fr, int fq) const {
;     ...
;         for (int n = 0; n < 2; ++n) {
;             const f32x4 cbv = *(const f32x4*)(cb + jc + n * 4), w0 = *(const f32x4*)(cw + jc + n * 4), w1 = *(const f32x4*)(cw + DFF + jc + n * 4), w2 = *(const f32x4*)(cw + 2 * DFF + jc + n * 4);
;             f32x4 p2, p1;
;             { const f32x4 x6 = acc[1][0][2][n], x7 = acc[1][0][3][n];
;               p2 = (f32x4){dpp_z<0x111>(x6.x), dpp_z<0x111>(x6.y), dpp_z<0x111>(x6.z), dpp_z<0x111>(x6.w)};
;               p1 = (f32x4){dpp_z<0x111>(x7.x), dpp_z<0x111>(x7.y), dpp_z<0x111>(x7.z), dpp_z<0x111>(x7.w)}; }
; #pragma unroll
;             for (int j = 0; j < 8; ++j) { const f32x4 x = acc[j >> 2][0][j & 3][n];
;                 const f32x4 cv = cbv + w0 * p2 + w1 * p1 + w2 * x;
;                 acc[j >> 2][1][j & 3][n] = silu4(cv) * acc[j >> 2][1][j & 3][n];
;                 p2 = p1; p1 = x; }
;         }
; #pragma unroll
;         for (int j = 0; j < 8; ++j) *(u32x4*)(ACT + (size_t)u.pm * (256 * DFF) + (size_t)(jc >> 6) * (256 * 64) + (lrow + j) * 64 + (jc & 63)) = pack8(acc[j >> 2][1][j & 3][0], acc[j >> 2][1][j & 3][1]);
	v_pk_fma_f32 v[46:47], v[88:89], v[22:23], v[46:47]
	v_pk_fma_f32 v[48:49], v[80:81], v[20:21], v[48:49]
	v_pk_fma_f32 v[46:47], v[78:79], v[18:19], v[46:47]
	v_mul_f32_e32 v52, 0xbfb8aa3b, v48
	v_mul_f32_e32 v50, 0xbfb8aa3b, v46
	v_mul_f32_e32 v51, 0xbfb8aa3b, v47
	v_mul_f32_e32 v53, 0xbfb8aa3b, v49
	v_exp_f32_e32 v50, v50
	v_exp_f32_e32 v51, v51
	v_exp_f32_e32 v52, v52
	v_exp_f32_e32 v53, v53
	v_add_f32_e32 v50, 1.0, v50
	v_add_f32_e32 v51, 1.0, v51
	v_add_f32_e32 v52, 1.0, v52
	v_add_f32_e32 v53, 1.0, v53
	v_rcp_f32_e32 v50, v50
	v_rcp_f32_e32 v51, v51
	v_rcp_f32_e32 v52, v52
	v_rcp_f32_e32 v53, v53
	v_exp_f32_e32 v135, v135
	v_pk_mul_f32 v[50:51], v[46:47], v[50:51]
	v_exp_f32_e32 v136, v136
	v_pk_mul_f32 v[48:49], v[48:49], v[52:53]
	v_pk_fma_f32 v[52:53], v[88:89], v[14:15], v[10:11]
	v_pk_mul_f32 v[46:47], v[92:93], v[48:49]
	v_pk_mul_f32 v[48:49], v[90:91], v[50:51]
	v_pk_fma_f32 v[50:51], v[86:87], v[16:17], v[12:13]
	v_pk_fma_f32 v[52:53], v[78:79], v[22:23], v[52:53]
	v_pk_fma_f32 v[50:51], v[80:81], v[24:25], v[50:51]
	v_pk_fma_f32 v[52:53], v[70:71], v[18:19], v[52:53]
	v_pk_fma_f32 v[50:51], v[72:73], v[20:21], v[50:51]
	v_mul_f32_e32 v54, 0xbfb8aa3b, v52
	v_mul_f32_e32 v56, 0xbfb8aa3b, v50
	v_mul_f32_e32 v57, 0xbfb8aa3b, v51
	v_mul_f32_e32 v55, 0xbfb8aa3b, v53
	v_exp_f32_e32 v56, v56
	v_exp_f32_e32 v57, v57
	v_exp_f32_e32 v54, v54
	v_exp_f32_e32 v55, v55
	v_add_f32_e32 v56, 1.0, v56
	v_add_f32_e32 v57, 1.0, v57
	v_add_f32_e32 v54, 1.0, v54
	v_add_f32_e32 v55, 1.0, v55
	v_rcp_f32_e32 v56, v56
	v_rcp_f32_e32 v57, v57
	v_rcp_f32_e32 v54, v54
	v_rcp_f32_e32 v55, v55
	v_exp_f32_e32 v137, v137
	v_pk_mul_f32 v[50:51], v[50:51], v[56:57]
	v_pk_fma_f32 v[56:57], v[78:79], v[14:15], v[10:11]
	v_pk_mul_f32 v[52:53], v[52:53], v[54:55]
	v_pk_fma_f32 v[54:55], v[80:81], v[16:17], v[12:13]
	v_pk_fma_f32 v[56:57], v[70:71], v[22:23], v[56:57]
	v_pk_fma_f32 v[10:11], v[70:71], v[14:15], v[10:11]
	v_pk_fma_f32 v[54:55], v[72:73], v[24:25], v[54:55]
	v_pk_fma_f32 v[56:57], v[6:7], v[18:19], v[56:57]
	v_pk_fma_f32 v[12:13], v[72:73], v[16:17], v[12:13]
	v_pk_fma_f32 v[6:7], v[6:7], v[22:23], v[10:11]
	v_pk_fma_f32 v[54:55], v[8:9], v[20:21], v[54:55]
	v_pk_fma_f32 v[8:9], v[8:9], v[24:25], v[12:13]
	v_pk_fma_f32 v[2:3], v[2:3], v[18:19], v[6:7]
	v_pk_fma_f32 v[4:5], v[4:5], v[20:21], v[8:9]
	v_mul_f32_e32 v6, 0xbfb8aa3b, v2
	v_mul_f32_e32 v7, 0xbfb8aa3b, v3
	v_exp_f32_e32 v6, v6
	v_exp_f32_e32 v7, v7
	v_mul_f32_e32 v8, 0xbfb8aa3b, v4
	v_mul_f32_e32 v9, 0xbfb8aa3b, v5
	v_exp_f32_e32 v8, v8
	v_exp_f32_e32 v9, v9
	v_add_f32_e32 v6, 1.0, v6
	v_add_f32_e32 v7, 1.0, v7
	v_rcp_f32_e32 v6, v6
	v_rcp_f32_e32 v7, v7
	v_add_f32_e32 v8, 1.0, v8
	v_add_f32_e32 v9, 1.0, v9
	v_rcp_f32_e32 v8, v8
	v_rcp_f32_e32 v9, v9
	v_pk_mul_f32 v[2:3], v[2:3], v[6:7]
	v_mul_f32_e32 v58, 0xbfb8aa3b, v56
	v_mul_f32_e32 v59, 0xbfb8aa3b, v57
	v_mul_f32_e32 v60, 0xbfb8aa3b, v54
	v_mul_f32_e32 v61, 0xbfb8aa3b, v55
	v_pk_mul_f32 v[4:5], v[4:5], v[8:9]
	v_pk_mul_f32 v[8:9], v[68:69], v[2:3]
	v_ashrrev_i32_e32 v2, 6, v170
	v_exp_f32_e32 v58, v58
	v_exp_f32_e32 v59, v59
	v_exp_f32_e32 v60, v60
	v_exp_f32_e32 v61, v61
	v_ashrrev_i32_e32 v3, 31, v2
	v_lshlrev_b64 v[10:11], 15, v[2:3]
	v_and_b32_e32 v12, 0x80, v0
	v_lshlrev_b32_e32 v12, 6, v12
	v_and_b32_e32 v248, 0x78, v0
	v_lshl_or_b32 v12, v248, 2, v12
	v_and_b32_e32 v14, 56, v170
	v_lshl_add_u64 v[10:11], s[10:11], 0, v[10:11]
	v_ashrrev_i32_e32 v13, 31, v12
	v_lshl_add_u64 v[10:11], v[12:13], 1, v[10:11]
	v_and_b32_e32 v248, 32, v14
	v_lshlrev_b32_e32 v248, 5, v248
	v_and_b32_e32 v0, 24, v14
	v_lshl_or_b32 v0, v0, 1, v248
	v_mov_b32_e32 v250, 0x1000
	v_mov_b32_e32 v251, 0
	v_add_f32_e32 v134, 1.0, v134
	v_add_f32_e32 v135, 1.0, v135
	v_add_f32_e32 v136, 1.0, v136
	v_add_f32_e32 v137, 1.0, v137
	v_add_f32_e32 v58, 1.0, v58
	v_add_f32_e32 v59, 1.0, v59
	v_add_f32_e32 v60, 1.0, v60
	v_add_f32_e32 v61, 1.0, v61
	v_pk_mul_f32 v[6:7], v[66:67], v[4:5]
	v_cvt_pk_bf16_f32 v2, v104, v105
	v_cvt_pk_bf16_f32 v3, v102, v103
	v_cvt_pk_bf16_f32 v4, v44, v45
	v_cvt_pk_bf16_f32 v5, v42, v43
	v_lshl_add_u64 v[10:11], v[10:11], 0, v[0:1]
	v_rcp_f32_e32 v134, v134
	v_rcp_f32_e32 v135, v135
	v_rcp_f32_e32 v136, v136
	v_rcp_f32_e32 v137, v137
	v_rcp_f32_e32 v58, v58
	v_rcp_f32_e32 v59, v59
	v_rcp_f32_e32 v60, v60
	v_rcp_f32_e32 v61, v61
	global_store_dwordx4 v[10:11], v[2:5], off
	v_pk_mul_f32 v[126:127], v[174:175], v[126:127]
	v_pk_mul_f32 v[128:129], v[172:173], v[128:129]
	v_cvt_pk_bf16_f32 v2, v112, v113
	v_cvt_pk_bf16_f32 v3, v110, v111
	v_cvt_pk_bf16_f32 v4, v34, v35
	v_cvt_pk_bf16_f32 v5, v36, v37
	global_store_dwordx4 v[10:11], v[2:5], off offset:2048
	v_pk_mul_f32 v[130:131], v[130:131], v[136:137]
	v_pk_mul_f32 v[132:133], v[132:133], v[134:135]
	v_cvt_pk_bf16_f32 v2, v116, v117
	v_cvt_pk_bf16_f32 v3, v114, v115
	v_cvt_pk_bf16_f32 v4, v32, v33
	v_cvt_pk_bf16_f32 v5, v30, v31
	v_lshl_add_u64 v[10:11], v[10:11], 0, v[250:251]
	global_store_dwordx4 v[10:11], v[2:5], off
	v_pk_mul_f32 v[50:51], v[84:85], v[50:51]
	v_pk_mul_f32 v[52:53], v[82:83], v[52:53]
	v_cvt_pk_bf16_f32 v2, v120, v121
	v_cvt_pk_bf16_f32 v3, v118, v119
	v_cvt_pk_bf16_f32 v4, v28, v29
	v_cvt_pk_bf16_f32 v5, v26, v27
	global_store_dwordx4 v[10:11], v[2:5], off offset:2048
	v_pk_mul_f32 v[54:55], v[54:55], v[60:61]
	v_pk_mul_f32 v[56:57], v[56:57], v[58:59]
	v_cvt_pk_bf16_f32 v2, v124, v125
	v_cvt_pk_bf16_f32 v3, v122, v123
	v_cvt_pk_bf16_f32 v4, v48, v49
	v_cvt_pk_bf16_f32 v5, v46, v47
	v_lshl_add_u64 v[10:11], v[10:11], 0, v[250:251]
	global_store_dwordx4 v[10:11], v[2:5], off
	v_pk_mul_f32 v[130:131], v[142:143], v[130:131]
	v_pk_mul_f32 v[132:133], v[144:145], v[132:133]
	v_cvt_pk_bf16_f32 v2, v128, v129
	v_cvt_pk_bf16_f32 v3, v126, v127
	v_cvt_pk_bf16_f32 v4, v52, v53
	v_cvt_pk_bf16_f32 v5, v50, v51
	v_pk_mul_f32 v[54:55], v[74:75], v[54:55]
	v_pk_mul_f32 v[56:57], v[76:77], v[56:57]
	global_store_dwordx4 v[10:11], v[2:5], off offset:2048
	s_mov_b64 s[10:11], -1
	s_nop 0
	v_cvt_pk_bf16_f32 v2, v132, v133
	v_cvt_pk_bf16_f32 v3, v130, v131
	v_cvt_pk_bf16_f32 v4, v56, v57
	v_cvt_pk_bf16_f32 v5, v54, v55
	v_lshl_add_u64 v[10:11], v[10:11], 0, v[250:251]
	global_store_dwordx4 v[10:11], v[2:5], off
	s_nop 1
	v_cvt_pk_bf16_f32 v2, v40, v41
	v_cvt_pk_bf16_f32 v3, v38, v39
	v_cvt_pk_bf16_f32 v4, v8, v9
	v_cvt_pk_bf16_f32 v5, v6, v7
	global_store_dwordx4 v[10:11], v[2:5], off offset:2048
	s_cbranch_vccnz .LBB0_1252
	s_andn2_b64 vcc, exec, s[12:13]
	s_cbranch_vccnz .LBB0_1251
	s_barrier
	s_branch .LBB0_1251
